# item setup waits only for the first K/V stage before entering the step loop
# speedup vs baseline: 1.0085x; 1.0058x over previous
; #define LAS __attribute__((address_space(3)))
; #define WAITBAR2() asm volatile("s_waitcnt vmcnt(2) lgkmcnt(0)\n\ts_barrier" ::: "memory")
; #define ISSUE_UP() do { STG_ISSUE(s_iss < sb_end ? s_iss : sb_end, slot_i); ++s_iss; slot_i = slot_i == NSTG - 1 ? 0 : slot_i + 1; } while (0)
; __device__ __forceinline__ void blk_B(int b, int hd, int chunk, const bf16_t* QK, const bf16_t* VT, bf16_t* mixed, LAS unsigned char* lds, const float* tblg, float wfar, float lam, float osc, const float* subln, int tid, int lane, int wave) {
;     const int q = lane & 31, h = lane >> 5, qb = chunk * 8 + wave;
;     LOAD_HEAD_TABLE(8 + hd);
;     const size_t tok0 = (size_t)b * SEQ;
;     const bf16_t* Qp = QK + (tok0 + qb * 32 + q) * 2048 + 1024 + hd * 64 + 8 * h;
;     bf16x8 qf[4];
; #pragma unroll
;     for (int s = 0; s < 4; ++s) qf[s] = *(const bf16x8*)(Qp + 16 * s);
;     const Stage st = make_stage(tid, QK, VT, tok0, 1280 + hd * 64, 512 + hd * 64);
;     LAS unsigned char* sb = lds + SBUF_OFF;
;     const int sb_end = chunk * 4 + 3;
;     int s_iss = 0, slot_i = 0, slot_c = 0;
;     ISSUE_UP(); ISSUE_UP();
;     WAITBAR2();
;     f32x16 oa0 = {}, oa1 = {}, ob0 = {}, ob1 = {}; float la = 0.f, lb = 0.f; bool scaled = false;
;     const LAS unsigned char* tb = LANE_TBL();
.LBB0_353:
	s_or_b64 exec, exec, s[0:1]
	s_ashr_i32 s18, s28, 5
	s_sub_i32 s19, 31, s18
	s_lshl_b32 s29, s19, 3
	s_add_i32 s29, s29, s25
	s_lshl_b32 s0, s28, 11
	s_and_b32 s30, s0, 0xe000
	s_lshl_b32 s0, s29, 5
	s_ashr_i32 s1, s0, 31
	s_add_u32 s0, s0, s30
	s_addc_u32 s1, s1, 0
	v_mov_b32_e32 v195, s1
	v_or_b32_e32 v194, s0, v172
	s_waitcnt vmcnt(0)
	v_lshlrev_b64 v[2:3], 12, v[194:195]
	s_lshl_b32 s28, s27, 6
	s_lshl_b32 s92, s27, 7
	v_readfirstlane_b32 s27, v170
	v_lshl_add_u64 v[2:3], s[80:81], 0, v[2:3]
	s_ashr_i32 s34, s27, 8
	v_lshl_add_u64 v[2:3], v[2:3], 0, s[92:93]
	v_lshlrev_b32_e32 v0, 1, v174
	s_lshl_b32 s0, s34, 5
	v_lshl_add_u64 v[2:3], v[2:3], 0, v[0:1]
	s_ashr_i32 s1, s0, 31
	v_or_b32_e32 v0, s30, v177
	global_load_dwordx4 v[130:133], v[2:3], off offset:2048
	global_load_dwordx4 v[134:137], v[2:3], off offset:2080
	global_load_dwordx4 v[138:141], v[2:3], off offset:2112
	global_load_dwordx4 v[142:145], v[2:3], off offset:2144
	s_ashr_i32 s31, s27, 6
	v_lshl_add_u64 v[2:3], s[0:1], 0, v[0:1]
	s_lshr_b32 s27, s27, 2
	v_lshlrev_b64 v[2:3], 12, v[2:3]
	v_and_or_b32 v4, s27, 32, v172
	v_lshl_add_u64 v[2:3], s[80:81], 0, v[2:3]
	s_and_b32 s35, s31, 3
	v_or_b32_e32 v4, s28, v4
	v_lshl_add_u64 v[2:3], v[2:3], 0, s[92:93]
	s_lshl_b32 s92, s35, 5
	v_lshlrev_b32_e32 v4, 17, v4
	v_mov_b32_e32 v5, v1
	v_lshl_add_u64 v[2:3], v[2:3], 0, s[92:93]
	v_lshl_add_u64 v[4:5], s[4:5], 0, v[4:5]
	s_lshl_b32 s92, s30, 1
	v_lshl_add_u64 v[4:5], v[4:5], 0, s[92:93]
	s_lshl_b32 s34, s34, 13
	s_lshl_b32 s35, s35, 10
	v_lshl_add_u64 v[4:5], s[0:1], 1, v[4:5]
	s_lshl_b32 s0, s31, 5
	v_lshlrev_b32_e32 v0, 1, v176
	s_or_b32 s34, s35, s34
	s_and_b32 s92, s0, 32
	v_lshl_add_u64 v[196:197], v[2:3], 0, v[0:1]
	v_lshl_add_u64 v[4:5], v[4:5], 0, s[92:93]
	s_add_i32 s76, s34, 0
	v_lshl_add_u64 v[2:3], v[196:197], 0, s[14:15]
	v_lshl_add_u64 v[4:5], v[4:5], 0, v[0:1]
	s_mov_b64 s[0:1], 0x4000000
	s_add_i32 m0, s76, 0x8900
	v_lshl_add_u64 v[198:199], v[4:5], 0, s[0:1]
	global_load_lds_dwordx4 v[2:3], off
	s_add_i32 m0, s76, 0x9900
	s_mov_b64 s[0:1], 0x40a00
	global_load_lds_dwordx4 v[198:199], off
	v_lshl_add_u64 v[2:3], v[196:197], 0, s[0:1]
	s_add_i32 m0, s76, 0xc900
	s_mov_b64 s[0:1], 0x4000080
	global_load_lds_dwordx4 v[2:3], off
	v_lshl_add_u64 v[2:3], v[4:5], 0, s[0:1]
	s_add_i32 m0, s76, 0xd900
	s_lshl_b32 s0, s19, 2
	global_load_lds_dwordx4 v[2:3], off
	s_mov_b64 s[0:1], 0x80a00
	v_lshl_add_u64 v[2:3], v[196:197], 0, s[0:1]
	s_add_i32 m0, s76, 0x10900
	s_mov_b64 s[0:1], 0x100
	global_load_lds_dwordx4 v[2:3], off
	v_lshl_add_u64 v[2:3], v[198:199], 0, s[0:1]
	s_add_i32 m0, s76, 0x11900
	s_mov_b64 s[0:1], 0xc0a00
	global_load_lds_dwordx4 v[2:3], off
	v_lshl_add_u64 v[2:3], v[196:197], 0, s[0:1]
	s_add_i32 m0, s76, 0x14900
	s_mov_b64 s[0:1], 0x180
	global_load_lds_dwordx4 v[2:3], off
	v_lshl_add_u64 v[2:3], v[198:199], 0, s[0:1]
	s_add_i32 m0, s76, 0x15900
	s_lshl_b32 s0, s19, 2
	global_load_lds_dwordx4 v[2:3], off
	s_waitcnt vmcnt(6) lgkmcnt(0)
	s_barrier
	v_mov_b32_e32 v16, v1
	v_mov_b32_e32 v17, v1
	s_or_b32 s78, s0, 3
	s_lshl_b32 s0, s18, 2
	v_mov_b32_e32 v0, v1
	v_mov_b32_e32 v2, v1
	v_mov_b32_e32 v3, v1
	v_mov_b32_e32 v4, v1
	v_mov_b32_e32 v5, v1
	v_mov_b32_e32 v6, v1
	v_mov_b32_e32 v7, v1
	v_mov_b32_e32 v8, v1
	v_mov_b32_e32 v9, v1
	v_mov_b32_e32 v10, v1
	v_mov_b32_e32 v11, v1
	v_mov_b32_e32 v12, v1
	v_mov_b32_e32 v13, v1
	v_mov_b32_e32 v14, v1
	v_mov_b32_e32 v15, v1
	v_mov_b64_e32 v[32:33], v[16:17]
	v_mov_b64_e32 v[64:65], v[16:17]
	v_mov_b64_e32 v[48:49], v[16:17]
	s_mov_b32 s77, 4
	s_mov_b32 s55, s54
	s_mov_b32 s56, s54
	s_mov_b32 s57, s54
	s_mov_b32 s58, s54
	s_mov_b32 s59, s54
	s_mov_b32 s60, s54
	s_mov_b32 s61, s54
	s_mov_b32 s62, s54
	s_mov_b32 s63, s54
	s_mov_b32 s64, s54
	s_mov_b32 s65, s54
	s_mov_b32 s66, s54
	s_mov_b32 s67, s54
	s_mov_b32 s68, s54
	s_mov_b32 s69, s54
	s_mov_b32 s70, s54
	s_mov_b32 s71, s54
	s_mov_b32 s79, 0
	s_sub_i32 s82, 0, s0
	v_lshl_add_u32 v206, s18, 10, v205
	s_mov_b64 s[18:19], 0
	s_movk_i32 s83, 0xff80
	s_mov_b32 s30, s29
	s_mov_b32 s31, 0
	v_mov_b64_e32 v[30:31], v[14:15]
	v_mov_b64_e32 v[28:29], v[12:13]
	v_mov_b64_e32 v[26:27], v[10:11]
	v_mov_b64_e32 v[24:25], v[8:9]
	v_mov_b64_e32 v[22:23], v[6:7]
	v_mov_b64_e32 v[20:21], v[4:5]
	v_mov_b64_e32 v[18:19], v[2:3]
	v_mov_b64_e32 v[62:63], v[14:15]
	v_mov_b64_e32 v[60:61], v[12:13]
	v_mov_b64_e32 v[58:59], v[10:11]
	v_mov_b64_e32 v[56:57], v[8:9]
	v_mov_b64_e32 v[54:55], v[6:7]
	v_mov_b64_e32 v[52:53], v[4:5]
	v_mov_b64_e32 v[50:51], v[2:3]
	v_mov_b64_e32 v[46:47], v[14:15]
	v_mov_b64_e32 v[44:45], v[12:13]
	v_mov_b64_e32 v[42:43], v[10:11]
	v_mov_b64_e32 v[40:41], v[8:9]
	v_mov_b64_e32 v[38:39], v[6:7]
	v_mov_b64_e32 v[36:37], v[4:5]
	v_mov_b64_e32 v[34:35], v[2:3]
	v_mov_b64_e32 v[200:201], v[0:1]
	s_waitcnt vmcnt(6)
	s_branch .LBB0_356

; #define LAS __attribute__((address_space(3)))
; #define WAITBAR2() asm volatile("s_waitcnt vmcnt(2) lgkmcnt(0)\n\ts_barrier" ::: "memory")
; #define ISSUE_UP() do { STG_ISSUE(s_iss < sb_end ? s_iss : sb_end, slot_i); ++s_iss; slot_i = slot_i == NSTG - 1 ? 0 : slot_i + 1; } while (0)
; __device__ __forceinline__ void blk_A(int b, int hd, int chunk  , const bf16_t* QK, const bf16_t* VT, bf16_t* mixed, LAS unsigned char* lds, const float* tblg, int tid, int lane, int wave) {
;     const int q = lane & 31, h = lane >> 5, qbA = chunk * 16 + wave, qbB = qbA + 8;
;     LOAD_HEAD_TABLE(hd);
;     const size_t tok0 = (size_t)b * SEQ;
;     bf16x8 qfA[4], qfB[4];
;     { const bf16_t* Qp = QK + (tok0 + qbA * 32 + q) * 2048 + hd * 64 + 8 * h;
; #pragma unroll
;       for (int s = 0; s < 4; ++s) { qfA[s] = *(const bf16x8*)(Qp + 16 * s); qfB[s] = *(const bf16x8*)(Qp + (size_t)8 * 32 * 2048 + 16 * s); } }
;     const Stage st = make_stage(tid, QK, VT, tok0, 512 + hd * 64, hd * 64);
;     LAS unsigned char* sb = lds + SBUF_OFF;
;     const int sb_end = chunk * 8 + 7, sb_lo = chunk * 8 > 32 ? chunk * 8 - 32 : 0;
;     int s_iss = sb_lo, slot_i = 0, slot_c = 0;
;     ...
;     ISSUE_UP(); ISSUE_UP();
;     WAITBAR2();
;     f32x16 oA0 = {}, oA1 = {}, oB0 = {}, oB1 = {}; float lA = 0.f, lB = 0.f;
;     const LAS unsigned char* tb = LANE_TBL();
.LBB0_405:
	s_or_b64 exec, exec, s[0:1]
	s_add_i32 s1, s28, 0xfffffc00
	s_lshr_b32 s0, s1, 6
	s_sub_i32 s31, 15, s0
	s_lshl_b32 s30, s31, 4
	s_add_i32 s30, s30, s25
	s_lshl_b32 s18, s28, 10
	s_and_b32 s34, s18, 0xe000
	s_lshl_b32 s18, s30, 5
	s_ashr_i32 s19, s18, 31
	s_add_u32 s18, s18, s34
	s_addc_u32 s19, s19, 0
	v_mov_b32_e32 v149, s19
	v_or_b32_e32 v148, s18, v172
	s_waitcnt vmcnt(0)
	v_lshlrev_b64 v[2:3], 12, v[148:149]
	v_lshl_add_u64 v[2:3], s[80:81], 0, v[2:3]
	s_lshl_b32 s92, s27, 7
	s_lshl_b32 s29, s27, 6
	v_lshl_add_u64 v[2:3], v[2:3], 0, s[92:93]
	v_lshlrev_b32_e32 v0, 1, v174
	v_readfirstlane_b32 s27, v170
	v_lshl_add_u64 v[2:3], v[2:3], 0, v[0:1]
	s_mov_b32 s18, 0x100000
	s_ashr_i32 s52, s27, 8
	v_add_co_u32_e32 v4, vcc, s18, v2
	s_lshl_b32 s18, s52, 5
	s_ashr_i32 s19, s18, 31
	v_or_b32_e32 v0, s34, v177
	v_addc_co_u32_e32 v5, vcc, 0, v3, vcc
	global_load_dwordx4 v[96:99], v[2:3], off
	global_load_dwordx4 v[100:103], v[2:3], off offset:32
	global_load_dwordx4 v[104:107], v[4:5], off
	global_load_dwordx4 v[108:111], v[4:5], off offset:32
	global_load_dwordx4 v[112:115], v[2:3], off offset:64
	global_load_dwordx4 v[116:119], v[2:3], off offset:96
	global_load_dwordx4 v[120:123], v[4:5], off offset:64
	global_load_dwordx4 v[124:127], v[4:5], off offset:96
	v_lshl_add_u64 v[2:3], s[18:19], 0, v[0:1]
	s_ashr_i32 s35, s27, 6
	v_lshlrev_b64 v[2:3], 12, v[2:3]
	v_lshl_add_u64 v[2:3], s[80:81], 0, v[2:3]
	s_and_b32 s53, s35, 3
	v_lshl_add_u64 v[2:3], v[2:3], 0, s[92:93]
	s_lshl_b32 s92, s53, 5
	v_lshl_add_u64 v[2:3], v[2:3], 0, s[92:93]
	v_lshlrev_b32_e32 v0, 1, v176
	s_lshr_b32 s27, s27, 2
	v_lshl_add_u64 v[150:151], v[2:3], 0, v[0:1]
	v_and_or_b32 v2, s27, 32, v172
	v_or_b32_e32 v2, s29, v2
	v_lshlrev_b32_e32 v2, 17, v2
	v_mov_b32_e32 v3, v1
	v_lshl_add_u64 v[2:3], s[4:5], 0, v[2:3]
	s_lshl_b32 s92, s34, 1
	v_lshl_add_u64 v[2:3], v[2:3], 0, s[92:93]
	v_lshl_add_u64 v[2:3], s[18:19], 1, v[2:3]
	s_lshl_b32 s18, s35, 5
	s_lshl_b32 s52, s52, 13
	s_lshl_b32 s53, s53, 10
	s_and_b32 s92, s18, 32
	s_lshl_b32 s18, s31, 3
	s_or_b32 s52, s53, s52
	s_or_b32 s27, s18, 7
	s_sub_i32 s18, s18, 32
	s_cmpk_lt_u32 s1, 0x2c0
	s_cselect_b32 s1, s18, 0
	v_lshl_add_u64 v[2:3], v[2:3], 0, s[92:93]
	s_min_i32 s92, s1, s27
	s_lshl_b64 s[18:19], s[92:93], 18
	v_lshl_add_u64 v[152:153], v[2:3], 0, v[0:1]
	v_lshl_add_u64 v[2:3], v[150:151], 0, s[18:19]
	s_add_i32 s31, s52, 0
	v_lshl_add_u64 v[2:3], v[2:3], 0, s[12:13]
	s_add_i32 m0, s31, 0x8900
	s_lshl_b32 s92, s92, 7
	s_or_b32 s18, s1, 1
	global_load_lds_dwordx4 v[2:3], off
	v_lshl_add_u64 v[2:3], v[152:153], 0, s[92:93]
	s_min_i32 s92, s18, s27
	s_add_i32 m0, s31, 0x9900
	s_lshl_b64 s[18:19], s[92:93], 18
	global_load_lds_dwordx4 v[2:3], off
	v_lshl_add_u64 v[2:3], v[150:151], 0, s[18:19]
	v_lshl_add_u64 v[2:3], v[2:3], 0, s[12:13]
	s_add_i32 m0, s31, 0xc900
	s_lshl_b32 s92, s92, 7
	global_load_lds_dwordx4 v[2:3], off
	v_lshl_add_u64 v[2:3], v[152:153], 0, s[92:93]
	s_add_i32 m0, s31, 0xd900
	s_cmp_gt_i32 s1, s27
	global_load_lds_dwordx4 v[2:3], off
	s_waitcnt vmcnt(2) lgkmcnt(0)
	s_barrier
	s_cbranch_scc1 .LBB0_419
	s_or_b32 s54, s1, 2
	s_lshl_b32 s52, s1, 1
	s_lshl_b32 s0, s0, 11
	s_lshl_b32 s1, s1, 8
	v_mov_b32_e32 v14, v1
	v_mov_b32_e32 v15, v1
	s_add_i32 s0, s0, s1
	v_mov_b32_e32 v0, v1
	v_mov_b32_e32 v2, v1
	v_mov_b32_e32 v3, v1
	v_mov_b32_e32 v4, v1
	v_mov_b32_e32 v5, v1
	v_mov_b32_e32 v6, v1
	v_mov_b32_e32 v7, v1
	v_mov_b32_e32 v8, v1
	v_mov_b32_e32 v9, v1
	v_mov_b32_e32 v10, v1
	v_mov_b32_e32 v11, v1
	v_mov_b32_e32 v12, v1
	v_mov_b32_e32 v13, v1
	v_mov_b64_e32 v[30:31], v[14:15]
	v_mov_b64_e32 v[46:47], v[14:15]
	v_mov_b64_e32 v[62:63], v[14:15]
	v_mov_b64_e32 v[78:79], v[14:15]
	s_add_i32 s34, s30, 8
	s_mov_b32 s35, 2
	v_add_u32_e32 v154, s0, v205
	s_mov_b32 s53, 0
	v_mov_b32_e32 v156, 0
	v_mov_b32_e32 v155, 0
	v_mov_b64_e32 v[28:29], v[12:13]
	v_mov_b64_e32 v[26:27], v[10:11]
	v_mov_b64_e32 v[24:25], v[8:9]
	v_mov_b64_e32 v[22:23], v[6:7]
	v_mov_b64_e32 v[20:21], v[4:5]
	v_mov_b64_e32 v[18:19], v[2:3]
	v_mov_b64_e32 v[16:17], v[0:1]
	v_mov_b64_e32 v[44:45], v[12:13]
	v_mov_b64_e32 v[42:43], v[10:11]
	v_mov_b64_e32 v[40:41], v[8:9]
	v_mov_b64_e32 v[38:39], v[6:7]
	v_mov_b64_e32 v[36:37], v[4:5]
	v_mov_b64_e32 v[34:35], v[2:3]
	v_mov_b64_e32 v[32:33], v[0:1]
	v_mov_b64_e32 v[60:61], v[12:13]
	v_mov_b64_e32 v[58:59], v[10:11]
	v_mov_b64_e32 v[56:57], v[8:9]
	v_mov_b64_e32 v[54:55], v[6:7]
	v_mov_b64_e32 v[52:53], v[4:5]
	v_mov_b64_e32 v[50:51], v[2:3]
	v_mov_b64_e32 v[48:49], v[0:1]
	v_mov_b64_e32 v[76:77], v[12:13]
	v_mov_b64_e32 v[74:75], v[10:11]
	v_mov_b64_e32 v[72:73], v[8:9]
	v_mov_b64_e32 v[70:71], v[6:7]
	v_mov_b64_e32 v[68:69], v[4:5]
	v_mov_b64_e32 v[66:67], v[2:3]
	v_mov_b64_e32 v[64:65], v[0:1]
	s_waitcnt vmcnt(2)
